# ret_out: software prefetch of next item staging+q loads during current item compute
# baseline (speedup 1.0000x reference)
.LBB0_744:
	s_andn2_b64 vcc, exec, s[0:1]
	s_cbranch_vccnz .LBB0_769
	s_cmpk_gt_i32 s30, 0x7e7
	s_cbranch_scc1 .LBB0_769
	v_lshlrev_b32_e32 v0, 4, v202
	v_and_b32_e32 v24, 0x70, v0
	v_readlane_b32 s1, v246, 0
	v_add_u32_e32 v0, 0x200, v202
	s_movk_i32 s0, 0x90
	s_waitcnt lgkmcnt(0)
	v_add_u32_e32 v1, s1, v24
	v_lshrrev_b32_e32 v28, 3, v0
	v_and_b32_e32 v2, 15, v202
	v_bfe_u32 v4, v202, 4, 2
	v_mov_b32_e32 v5, s1
	v_lshrrev_b32_e32 v0, 2, v202
	s_movk_i32 s1, 0xf0
	v_and_or_b32 v42, v0, s1, v2
	v_mad_u32_u24 v8, v2, s0, v5
	v_lshlrev_b32_e32 v2, 2, v4
	v_lshlrev_b32_e32 v0, 3, v4
	v_lshlrev_b32_e32 v9, 4, v4
	v_sub_u32_e32 v4, v42, v2
	v_cmp_lt_i32_e32 vcc, -1, v4
	v_cvt_f32_u32_e32 v43, v4
	v_xad_u32 v4, v2, -1, v42
	v_cmp_lt_i32_e64 s[4:5], -1, v4
	v_cvt_f32_u32_e32 v44, v4
	v_or_b32_e32 v4, 3, v2
	v_sub_u32_e32 v4, v42, v4
	v_cmp_lt_i32_e64 s[6:7], -1, v4
	v_cvt_f32_u32_e32 v46, v4
	v_or_b32_e32 v4, 17, v2
	v_sub_u32_e32 v11, v42, v4
	v_or_b32_e32 v4, 19, v2
	v_sub_u32_e32 v13, v42, v4
	v_or_b32_e32 v4, 33, v2
	v_sub_u32_e32 v15, v42, v4
	v_or_b32_e32 v4, 35, v2
	v_sub_u32_e32 v17, v42, v4
	v_or_b32_e32 v4, 49, v2
	v_sub_u32_e32 v19, v42, v4
	v_or_b32_e32 v4, 51, v2
	v_sub_u32_e32 v21, v42, v4
	v_or_b32_e32 v4, 0x41, v2
	v_sub_u32_e32 v23, v42, v4
	v_or_b32_e32 v4, 0x43, v2
	v_sub_u32_e32 v34, v42, v4
	v_or_b32_e32 v4, 0x51, v2
	v_sub_u32_e32 v36, v42, v4
	v_or_b32_e32 v4, 0x53, v2
	v_sub_u32_e32 v38, v42, v4
	v_or_b32_e32 v4, 0x61, v2
	v_sub_u32_e32 v40, v42, v4
	v_or_b32_e32 v4, 0x63, v2
	v_sub_u32_e32 v78, v42, v4
	v_or_b32_e32 v4, 0x71, v2
	v_or_b32_e32 v30, 0x42, v2
	v_sub_u32_e32 v80, v42, v4
	v_or_b32_e32 v4, 0x73, v2
	v_sub_u32_e32 v35, v42, v30
	v_or_b32_e32 v30, 0x50, v2
	v_sub_u32_e32 v82, v42, v4
	v_bfe_u32 v4, v202, 2, 2
	v_sub_u32_e32 v37, v42, v30
	v_or_b32_e32 v30, 0x52, v2
	v_or_b32_e32 v4, v2, v4
	s_movk_i32 s1, 0x7f
	v_sub_u32_e32 v39, v42, v30
	v_or_b32_e32 v30, 0x60, v2
	v_mad_u32_u24 v84, v4, s0, v5
	v_lshlrev_b32_e32 v4, 3, v202
	v_cmp_lt_u32_e64 s[12:13], s1, v202
	s_movk_i32 s1, 0xbf
	v_sub_u32_e32 v41, v42, v30
	v_or_b32_e32 v30, 0x62, v2
	v_and_b32_e32 v85, 24, v4
	v_add_u32_e32 v4, 1, v42
	v_cmp_lt_u32_e64 s[14:15], s1, v202
	s_movk_i32 s1, 0xff
	v_sub_u32_e32 v79, v42, v30
	v_or_b32_e32 v30, 0x70, v2
	v_cvt_f32_u32_e32 v75, v4
	v_mbcnt_lo_u32_b32 v4, -1, 0
	v_cmp_lt_u32_e64 s[16:17], s1, v202
	s_movk_i32 s1, 0x13f
	v_sub_u32_e32 v81, v42, v30
	v_or_b32_e32 v30, 0x72, v2
	v_mbcnt_hi_u32_b32 v4, -1, v4
	v_lshrrev_b32_e32 v26, 3, v202
	v_cmp_lt_u32_e64 s[18:19], s1, v202
	s_movk_i32 s1, 0x17f
	v_sub_u32_e32 v83, v42, v30
	v_and_b32_e32 v30, 64, v4
	v_mad_u32_u24 v7, v26, s0, v5
	v_cmp_lt_u32_e64 s[82:83], s1, v202
	s_movk_i32 s1, 0x1bf
	v_xor_b32_e32 v5, 16, v4
	v_add_u32_e32 v30, 64, v30
	v_cmp_lt_u32_e64 s[84:85], s1, v202
	v_cmp_lt_i32_e64 s[0:1], v5, v30
	s_add_u32 s94, s22, 0x95a4000
	v_mov_b32_e32 v25, 0
	v_cndmask_b32_e64 v5, v4, v5, s[0:1]
	v_lshlrev_b32_e32 v76, 2, v5
	v_xor_b32_e32 v5, 32, v4
	v_cmp_lt_i32_e64 s[0:1], v5, v30
	v_or_b32_e32 v10, 2, v2
	s_addc_u32 s95, s23, 0
	v_cndmask_b32_e64 v4, v4, v5, s[0:1]
	v_sub_u32_e32 v10, v42, v10
	v_lshlrev_b32_e32 v77, 2, v4
	v_lshl_add_u64 v[4:5], s[22:23], 0, v[24:25]
	s_mov_b64 s[0:1], 0xb6a4000
	s_add_u32 s96, s22, 0xf8a4000
	s_mov_b32 s86, s30
	v_mov_b32_e32 v27, v25
	v_cvt_f32_u32_e32 v45, v10
	v_cmp_lt_i32_e64 s[8:9], -1, v10
	v_or_b32_e32 v10, 16, v2
	v_or_b32_e32 v12, 18, v2
	v_or_b32_e32 v14, 32, v2
	v_or_b32_e32 v16, 34, v2
	v_or_b32_e32 v18, 48, v2
	v_or_b32_e32 v20, 50, v2
	v_or_b32_e32 v22, 64, v2
	v_lshl_add_u64 v[30:31], v[4:5], 0, s[0:1]
	s_mov_b64 s[0:1], 0xd7a4000
	s_addc_u32 s97, s23, 0
	s_ashr_i32 s87, s86, 31
	v_sub_u32_e32 v10, v42, v10
	v_sub_u32_e32 v12, v42, v12
	v_sub_u32_e32 v14, v42, v14
	v_sub_u32_e32 v16, v42, v16
	v_sub_u32_e32 v18, v42, v18
	v_sub_u32_e32 v20, v42, v20
	v_sub_u32_e32 v22, v42, v22
	v_lshl_add_u64 v[32:33], v[4:5], 0, s[0:1]
	s_lshl_b64 s[0:1], s[86:87], 13
	v_lshlrev_b64 v[4:5], 7, v[26:27]
	v_cvt_f32_u32_e32 v47, v10
	v_cvt_f32_u32_e32 v48, v11
	v_cvt_f32_u32_e32 v49, v12
	v_cvt_f32_u32_e32 v50, v13
	v_cvt_f32_u32_e32 v51, v14
	v_cvt_f32_u32_e32 v52, v15
	v_cvt_f32_u32_e32 v53, v16
	v_cvt_f32_u32_e32 v54, v17
	v_cvt_f32_u32_e32 v55, v18
	v_cvt_f32_u32_e32 v56, v19
	v_cvt_f32_u32_e32 v57, v20
	v_cvt_f32_u32_e32 v58, v21
	v_cvt_f32_u32_e32 v59, v22
	v_cvt_f32_u32_e32 v60, v23
	v_cvt_f32_u32_e32 v61, v35
	v_cvt_f32_u32_e32 v62, v34
	v_cvt_f32_u32_e32 v63, v37
	v_cvt_f32_u32_e32 v64, v36
	v_cvt_f32_u32_e32 v65, v39
	v_cvt_f32_u32_e32 v66, v38
	v_cvt_f32_u32_e32 v67, v41
	v_cvt_f32_u32_e32 v68, v40
	v_cvt_f32_u32_e32 v69, v79
	v_cvt_f32_u32_e32 v70, v78
	v_cvt_f32_u32_e32 v71, v81
	v_cvt_f32_u32_e32 v72, v80
	v_cvt_f32_u32_e32 v73, v83
	v_cvt_f32_u32_e32 v74, v82
	v_lshl_add_u64 v[4:5], s[0:1], 0, v[4:5]
	v_or_b32_e32 v4, v4, v24
	v_mul_u32_u24_e32 v3, 0x90, v26
	v_mul_u32_u24_e32 v6, 0x90, v28
	v_lshl_add_u64 v[4:5], s[22:23], 0, v[4:5]
	s_mov_b64 s[0:1], 0x17ba4000
	v_mov_b32_e32 v29, v25
	v_cmp_lt_u32_e64 s[10:11], 63, v202
	s_mov_b32 s3, 0
	v_cmp_lt_i32_e64 s[24:25], -1, v13
	v_cmp_lt_i32_e64 s[26:27], -1, v12
	v_cmp_lt_i32_e64 s[28:29], -1, v11
	v_cmp_lt_i32_e64 s[30:31], -1, v10
	v_cmp_lt_i32_e64 s[34:35], -1, v17
	v_cmp_lt_i32_e64 s[36:37], -1, v16
	v_cmp_lt_i32_e64 s[38:39], -1, v15
	v_cmp_lt_i32_e64 s[40:41], -1, v14
	v_cmp_lt_i32_e64 s[42:43], -1, v21
	v_cmp_lt_i32_e64 s[44:45], -1, v20
	v_cmp_lt_i32_e64 s[46:47], -1, v19
	v_cmp_lt_i32_e64 s[48:49], -1, v18
	v_cmp_lt_i32_e64 s[50:51], -1, v34
	v_cmp_lt_i32_e64 s[52:53], -1, v35
	v_cmp_lt_i32_e64 s[54:55], -1, v23
	v_cmp_lt_i32_e64 s[56:57], -1, v22
	v_cmp_lt_i32_e64 s[58:59], -1, v38
	v_cmp_lt_i32_e64 s[60:61], -1, v39
	v_cmp_lt_i32_e64 s[62:63], -1, v36
	v_cmp_lt_i32_e64 s[64:65], -1, v37
	v_cmp_lt_i32_e64 s[66:67], -1, v78
	v_cmp_lt_i32_e64 s[68:69], -1, v79
	v_cmp_lt_i32_e64 s[70:71], -1, v40
	v_cmp_lt_i32_e64 s[72:73], -1, v41
	v_cmp_lt_i32_e64 s[74:75], -1, v82
	v_cmp_lt_i32_e64 s[76:77], -1, v83
	v_cmp_lt_i32_e64 s[78:79], -1, v80
	v_cmp_lt_i32_e64 s[80:81], -1, v81
	v_lshl_add_u64 v[34:35], v[4:5], 0, s[0:1]
	s_lshl_b32 s33, s86, 7
	v_mov_b32_e32 v27, 0x42800000
	v_add_u32_e32 v78, v1, v3
	v_add_u32_e32 v79, v1, v6
	v_add_u32_e32 v80, v7, v24
	v_lshlrev_b32_e32 v36, 1, v0
	v_mov_b32_e32 v37, v25
	v_add_u32_e32 v81, v8, v9
	v_mov_b32_e32 v82, 0x358637bd
	v_lshlrev_b32_e32 v38, 1, v2
	v_add_u32_e32 v83, v84, v85
	s_mov_b32 s92, s86
	s_mov_b32 s91, 0
	s_branch .LBB0_748

.LBB0_748:
	s_bfe_u32 s87, s86, 0x30005
	v_cvt_f32_ubyte0_e32 v0, s87
	v_sub_f32_e32 v0, 0xc0a00000, v0
	s_mov_b32 s0, 0xc2fc0000
	v_cmp_gt_f32_e64 s[0:1], s0, v0
	s_ashr_i32 s88, s86, 8
	s_waitcnt vmcnt(0)
	v_cndmask_b32_e64 v1, 0, v27, s[0:1]
	v_add_f32_e32 v0, v0, v1
	v_exp_f32_e32 v0, v0
	s_and_b64 s[0:1], s[0:1], exec
	s_cselect_b32 s0, 0xffffffc0, 0
	s_ashr_i32 s89, s88, 31
	v_ldexp_f32 v0, v0, s0
	s_lshl_b64 s[0:1], s[88:89], 12
	s_and_b32 s90, s33, 0xf80
	s_or_b32 s88, s0, s90
	v_sub_f32_e32 v10, 1.0, v0
	s_lshl_b32 s2, s87, 7
	v_mov_b32_e32 v1, s1
	v_or_b32_e32 v0, s88, v26
	v_lshl_add_u64 v[4:5], v[30:31], 0, s[2:3]
	v_lshlrev_b64 v[8:9], 10, v[0:1]
	v_lshl_add_u64 v[0:1], v[4:5], 0, v[8:9]
	s_cmp_eq_u32 s91, 1
	s_cbranch_scc1 .Lro2_pfpath
	global_load_dwordx4 v[120:123], v[0:1], off nt
	v_lshl_add_u64 v[6:7], v[32:33], 0, s[2:3]
	s_mov_b32 s89, s1
	v_add_u32_e32 v24, s90, v42
	v_lshl_add_u64 v[40:41], s[0:1], 0, v[24:25]
	v_log_f32_e32 v39, v10
	v_lshl_add_u64 v[0:1], v[6:7], 0, v[8:9]
	global_load_dwordx4 v[124:127], v[0:1], off nt
	v_lshl_add_u64 v[0:1], s[88:89], 0, v[28:29]
	v_lshlrev_b64 v[8:9], 10, v[0:1]
	v_lshl_add_u64 v[0:1], v[4:5], 0, v[8:9]
	global_load_dwordx4 v[128:131], v[0:1], off nt
	v_lshl_add_u64 v[0:1], v[6:7], 0, v[8:9]
	global_load_dwordx4 v[132:135], v[0:1], off nt
	global_load_dwordx4 v[136:139], v[34:35], off nt
	v_lshlrev_b64 v[0:1], 10, v[40:41]
	v_lshl_add_u64 v[0:1], s[94:95], 0, v[0:1]
	v_lshl_add_u64 v[0:1], v[0:1], 0, s[2:3]
	v_lshl_add_u64 v[0:1], v[0:1], 0, v[36:37]
	global_load_dwordx4 v[4:7], v[0:1], off nt
	s_nop 0
	global_load_dwordx4 v[0:3], v[0:1], off offset:64 nt
	s_branch .Lro2_join
.Lro2_pfpath:
	v_add_u32_e32 v24, s90, v42
	v_lshl_add_u64 v[40:41], s[0:1], 0, v[24:25]
	v_log_f32_e32 v39, v10
	s_mov_b32 s89, s1
	v_mov_b32_e32 v4, v152
	v_mov_b32_e32 v5, v153
	v_mov_b32_e32 v6, v154
	v_mov_b32_e32 v7, v155
	v_mov_b32_e32 v0, v156
	v_mov_b32_e32 v1, v157
	v_mov_b32_e32 v2, v158
	v_mov_b32_e32 v3, v159
.Lro2_join:
	s_barrier
	s_waitcnt vmcnt(6)
	ds_write_b128 v78, v[120:123]
	s_waitcnt vmcnt(5)
	ds_write_b128 v78, v[124:127] offset:18432
	s_waitcnt vmcnt(4)
	ds_write_b128 v79, v[128:131]
	s_waitcnt vmcnt(3)
	ds_write_b128 v79, v[132:135] offset:18432
	s_waitcnt vmcnt(2)
	ds_write_b128 v80, v[136:139] offset:36864
	s_waitcnt lgkmcnt(0)
	s_barrier
	ds_read_b128 v[8:11], v81
	ds_read_b128 v[12:15], v81 offset:64
	s_waitcnt vmcnt(1) lgkmcnt(1)
	v_mfma_f32_16x16x32_bf16 v[8:11], v[8:11], v[4:7], 0
	s_waitcnt vmcnt(0) lgkmcnt(0)
	v_mfma_f32_16x16x32_bf16 v[8:11], v[12:15], v[0:3], v[8:11]
	v_lshlrev_b64 v[150:151], 10, v[40:41]
	v_lshl_add_u64 v[150:151], v[150:151], 0, s[96:97]
	v_mov_b32_e32 v148, v38
	v_mov_b32_e32 v149, 0
	v_lshl_add_u64 v[150:151], v[150:151], 0, s[2:3]
	v_lshl_add_u64 v[150:151], v[150:151], 0, v[148:149]
	global_load_dwordx2 v[140:141], v[150:151], off nt
	global_load_dwordx2 v[142:143], v[150:151], off offset:32 nt
	global_load_dwordx2 v[144:145], v[150:151], off offset:64 nt
	global_load_dwordx2 v[146:147], v[150:151], off offset:96 nt
	s_mov_b32 s91, 0
	s_cmpk_gt_i32 s86, 0x6ef
	s_cbranch_scc1 .Lro2_nopf
	s_add_i32 s98, s86, 0xf8
	s_bfe_u32 s32, s98, 0x30005
	s_lshl_b32 s32, s32, 7
	s_ashr_i32 s100, s98, 8
	s_ashr_i32 s101, s100, 31
	s_lshl_b64 s[100:101], s[100:101], 12
	s_add_i32 s93, s33, 0x7c00
	s_and_b32 s93, s93, 0xf80
	s_or_b32 s98, s100, s93
	v_mov_b32_e32 v160, s32
	v_mov_b32_e32 v161, 0
	v_mov_b32_e32 v163, s101
	v_or_b32_e32 v162, s98, v26
	v_lshlrev_b64 v[162:163], 10, v[162:163]
	v_lshl_add_u64 v[164:165], v[30:31], 0, v[160:161]
	v_lshl_add_u64 v[166:167], v[32:33], 0, v[160:161]
	v_lshl_add_u64 v[168:169], v[164:165], 0, v[162:163]
	global_load_dwordx4 v[120:123], v[168:169], off nt
	v_lshl_add_u64 v[168:169], v[166:167], 0, v[162:163]
	global_load_dwordx4 v[124:127], v[168:169], off nt
	v_mov_b32_e32 v162, s98
	v_mov_b32_e32 v163, s101
	v_lshl_add_u64 v[162:163], v[162:163], 0, v[28:29]
	v_lshlrev_b64 v[162:163], 10, v[162:163]
	v_lshl_add_u64 v[168:169], v[164:165], 0, v[162:163]
	global_load_dwordx4 v[128:131], v[168:169], off nt
	v_lshl_add_u64 v[168:169], v[166:167], 0, v[162:163]
	global_load_dwordx4 v[132:135], v[168:169], off nt
	s_mov_b32 s98, 0x1f0000
	s_mov_b32 s99, 0
	v_lshl_add_u64 v[168:169], v[34:35], 0, s[98:99]
	global_load_dwordx4 v[136:139], v[168:169], off nt
	v_add_u32_e32 v170, s93, v42
	v_mov_b32_e32 v171, v25
	v_mov_b32_e32 v172, s100
	v_mov_b32_e32 v173, s101
	v_lshl_add_u64 v[170:171], v[172:173], 0, v[170:171]
	v_lshlrev_b64 v[170:171], 10, v[170:171]
	v_lshl_add_u64 v[170:171], s[94:95], 0, v[170:171]
	v_lshl_add_u64 v[170:171], v[170:171], 0, v[160:161]
	v_lshl_add_u64 v[170:171], v[170:171], 0, v[36:37]
	global_load_dwordx4 v[152:155], v[170:171], off nt
	global_load_dwordx4 v[156:159], v[170:171], off offset:64 nt
	s_mov_b32 s91, 1
.Lro2_nopf:
	v_mov_b32_e32 v12, 0
	v_mov_b32_e32 v13, 0
	v_mov_b32_e32 v14, 0
	v_mov_b32_e32 v15, 0
	s_and_saveexec_b64 s[0:1], s[10:11]
	s_cbranch_execz .LBB0_750
	ds_read_b128 v[12:15], v81 offset:2304
	ds_read_b128 v[16:19], v81 offset:2368
	s_waitcnt lgkmcnt(1)
	v_mfma_f32_16x16x32_bf16 v[12:15], v[12:15], v[4:7], 0
	s_waitcnt lgkmcnt(0)
	v_mfma_f32_16x16x32_bf16 v[12:15], v[16:19], v[0:3], v[12:15]
	v_mul_f32_e32 v16, v39, v47
	v_mul_f32_e32 v17, v39, v48
	v_mul_f32_e32 v18, v39, v49
	v_mul_f32_e32 v19, v39, v50
	v_exp_f32_e32 v16, v16
	v_exp_f32_e32 v17, v17
	v_exp_f32_e32 v18, v18
	v_exp_f32_e32 v19, v19
	v_pk_mul_f32 v[12:13], v[16:17], v[12:13]
	s_nop 0
	v_cndmask_b32_e64 v12, 0, v12, s[30:31]
	v_pk_mul_f32 v[14:15], v[18:19], v[14:15]
	v_cndmask_b32_e64 v13, 0, v13, s[28:29]
	v_cndmask_b32_e64 v14, 0, v14, s[26:27]
	v_cndmask_b32_e64 v15, 0, v15, s[24:25]

	.amdhsa_kernel _Z10fwd_kernel6Params
		.amdhsa_group_segment_fixed_size 147456
		.amdhsa_private_segment_fixed_size 0
		.amdhsa_kernarg_size 472
		.amdhsa_user_sgpr_count 2
		.amdhsa_user_sgpr_dispatch_ptr 0
		.amdhsa_user_sgpr_queue_ptr 0
		.amdhsa_user_sgpr_kernarg_segment_ptr 1
		.amdhsa_user_sgpr_dispatch_id 0
		.amdhsa_user_sgpr_kernarg_preload_length 0
		.amdhsa_user_sgpr_kernarg_preload_offset 0
		.amdhsa_user_sgpr_private_segment_size 0
		.amdhsa_uses_dynamic_stack 0
		.amdhsa_enable_private_segment 0
		.amdhsa_system_sgpr_workgroup_id_x 1
		.amdhsa_system_sgpr_workgroup_id_y 0
		.amdhsa_system_sgpr_workgroup_id_z 0
		.amdhsa_system_sgpr_workgroup_info 0
		.amdhsa_system_vgpr_workitem_id 2
		.amdhsa_next_free_vgpr 256
		.amdhsa_next_free_sgpr 102
		.amdhsa_accum_offset 256
		.amdhsa_reserve_vcc 1
		.amdhsa_float_round_mode_32 0
		.amdhsa_float_round_mode_16_64 0
		.amdhsa_float_denorm_mode_32 3
		.amdhsa_float_denorm_mode_16_64 3
		.amdhsa_dx10_clamp 1
		.amdhsa_ieee_mode 1
		.amdhsa_fp16_overflow 0
		.amdhsa_tg_split 0
		.amdhsa_exception_fp_ieee_invalid_op 0
		.amdhsa_exception_fp_denorm_src 0
		.amdhsa_exception_fp_ieee_div_zero 0
		.amdhsa_exception_fp_ieee_overflow 0
		.amdhsa_exception_fp_ieee_underflow 0
		.amdhsa_exception_fp_ieee_inexact 0
		.amdhsa_exception_int_div_zero 0
	.end_amdhsa_kernel

amdhsa.kernels:
  - .agpr_count:     0
    .args:
      - .offset:         0
        .size:           216
        .value_kind:     by_value
      - .offset:         216
        .size:           4
        .value_kind:     hidden_block_count_x
      - .offset:         220
        .size:           4
        .value_kind:     hidden_block_count_y
      - .offset:         224
        .size:           4
        .value_kind:     hidden_block_count_z
      - .offset:         228
        .size:           2
        .value_kind:     hidden_group_size_x
      - .offset:         230
        .size:           2
        .value_kind:     hidden_group_size_y
      - .offset:         232
        .size:           2
        .value_kind:     hidden_group_size_z
      - .offset:         234
        .size:           2
        .value_kind:     hidden_remainder_x
      - .offset:         236
        .size:           2
        .value_kind:     hidden_remainder_y
      - .offset:         238
        .size:           2
        .value_kind:     hidden_remainder_z
      - .offset:         256
        .size:           8
        .value_kind:     hidden_global_offset_x
      - .offset:         264
        .size:           8
        .value_kind:     hidden_global_offset_y
      - .offset:         272
        .size:           8
        .value_kind:     hidden_global_offset_z
      - .offset:         280
        .size:           2
        .value_kind:     hidden_grid_dims
      - .offset:         304
        .size:           8
        .value_kind:     hidden_multigrid_sync_arg
    .group_segment_fixed_size: 147456
    .kernarg_segment_align: 8
    .kernarg_segment_size: 472
    .language:       OpenCL C
    .language_version:
      - 2
      - 0
    .max_flat_workgroup_size: 512
    .name:           _Z10fwd_kernel6Params
    .private_segment_fixed_size: 0
    .sgpr_count:     108
    .sgpr_spill_count: 199
    .symbol:         _Z10fwd_kernel6Params.kd
    .uniform_work_group_size: 1
    .uses_dynamic_stack: false
    .vgpr_count:     256
    .vgpr_spill_count: 0
    .wavefront_size: 64
